# window and banded units: the cross-lane max reduction runs only when some lane's local max exceeds the running max (same rescale condition)
# baseline (speedup 1.0000x reference)
.Lw_pfgos:
	s_add_i32 s2, s18, 7
	s_and_b32 s2, s2, 7
	s_lshl_b32 s0, s2, 13
	s_add_i32 m0, s0, s23
	s_lshl_b32 s0, s11, 11
	s_add_u32 s16, s12, s0
	s_addc_u32 s17, s13, 0
	global_load_lds_dwordx4 v96, s[16:17]
	s_lshl_b32 s0, s18, 13
	v_add_u32_e32 v40, s0, v97
	ds_read_b128 v[56:59], v40 offset:0
	ds_read_b128 v[60:63], v40 offset:1024
	ds_read_b128 v[68:71], v40 offset:2048
	ds_read_b128 v[72:75], v40 offset:3072
	ds_read_b128 v[76:79], v40 offset:4096
	ds_read_b128 v[80:83], v40 offset:5120
	ds_read_b128 v[84:87], v40 offset:6144
	ds_read_b128 v[92:95], v40 offset:7168
	s_add_i32 s18, s18, 1
	s_and_b32 s18, s18, 7
	s_waitcnt lgkmcnt(4)
	v_mfma_f32_16x16x32_bf16 v[32:35], v[56:59], v[16:19], 0
	v_mfma_f32_16x16x32_bf16 v[36:39], v[68:71], v[16:19], 0
	v_mfma_f32_16x16x32_bf16 v[32:35], v[60:63], v[20:23], v[32:35]
	v_mfma_f32_16x16x32_bf16 v[36:39], v[72:75], v[20:23], v[36:39]
	v_mfma_f32_16x16x32_bf16 v[144:147], v[56:59], v[120:123], 0
	v_mfma_f32_16x16x32_bf16 v[148:151], v[68:71], v[120:123], 0
	v_mfma_f32_16x16x32_bf16 v[144:147], v[60:63], v[124:127], v[144:147]
	v_mfma_f32_16x16x32_bf16 v[148:151], v[72:75], v[124:127], v[148:151]
	ds_read_b32 v40, v50 offset:76
	ds_read_b32 v41, v50 offset:72
	ds_read_b32 v42, v50 offset:68
	ds_read_b32 v43, v50 offset:64
	ds_read_b32 v44, v50 offset:12
	ds_read_b32 v45, v50 offset:8
	ds_read_b32 v46, v50 offset:4
	ds_read_b32 v47, v50 offset:0
	ds_read_b32 v152, v50 offset:140
	ds_read_b32 v153, v50 offset:136
	ds_read_b32 v154, v50 offset:132
	ds_read_b32 v155, v50 offset:128
	ds_read_b32 v156, v50 offset:76
	ds_read_b32 v157, v50 offset:72
	ds_read_b32 v158, v50 offset:68
	ds_read_b32 v159, v50 offset:64
	v_add_u32_e32 v50, 0xffffff80, v50
	s_waitcnt lgkmcnt(0)
	v_pk_fma_f32 v[32:33], v[32:33], s[40:41], v[40:41] op_sel_hi:[1,0,1]
	v_pk_fma_f32 v[34:35], v[34:35], s[40:41], v[42:43] op_sel_hi:[1,0,1]
	v_pk_fma_f32 v[36:37], v[36:37], s[40:41], v[44:45] op_sel_hi:[1,0,1]
	v_pk_fma_f32 v[38:39], v[38:39], s[40:41], v[46:47] op_sel_hi:[1,0,1]
	v_max3_f32 v40, v32, v33, v34
	v_max3_f32 v41, v35, v36, v37
	v_max3_f32 v40, v40, v38, v39
	v_max_f32_e32 v40, v40, v41
	v_cmp_gt_f32_e32 vcc, v40, v48
	s_cbranch_vccz .Lw_norescA
	v_mov_b32_e32 v41, v40
	s_nop 1
	v_permlane16_swap_b32_e32 v41, v40
	v_max_f32_e32 v40, v40, v41
	v_mov_b32_e32 v41, v40
	s_nop 1
	v_permlane32_swap_b32_e32 v41, v40
	v_max_f32_e32 v42, v40, v41
	v_max_f32_e32 v42, v48, v42
	v_sub_f32_e32 v40, v48, v42
	v_exp_f32_e32 v40, v40
	v_mov_b32_e32 v48, v42
	s_nop 0
	v_pk_mul_f32 v[0:1], v[0:1], v[40:41] op_sel_hi:[1,0]
	v_pk_mul_f32 v[2:3], v[2:3], v[40:41] op_sel_hi:[1,0]
	v_pk_mul_f32 v[4:5], v[4:5], v[40:41] op_sel_hi:[1,0]
	v_pk_mul_f32 v[6:7], v[6:7], v[40:41] op_sel_hi:[1,0]
	v_pk_mul_f32 v[8:9], v[8:9], v[40:41] op_sel_hi:[1,0]
	v_pk_mul_f32 v[10:11], v[10:11], v[40:41] op_sel_hi:[1,0]
	v_pk_mul_f32 v[12:13], v[12:13], v[40:41] op_sel_hi:[1,0]
	v_pk_mul_f32 v[14:15], v[14:15], v[40:41] op_sel_hi:[1,0]
	v_mul_f32_e32 v49, v49, v40
.Lw_norescA:
	v_pk_add_f32 v[32:33], v[32:33], v[48:49] op_sel_hi:[1,0] neg_lo:[0,1] neg_hi:[0,1]
	v_pk_add_f32 v[34:35], v[34:35], v[48:49] op_sel_hi:[1,0] neg_lo:[0,1] neg_hi:[0,1]
	v_pk_add_f32 v[36:37], v[36:37], v[48:49] op_sel_hi:[1,0] neg_lo:[0,1] neg_hi:[0,1]
	v_pk_add_f32 v[38:39], v[38:39], v[48:49] op_sel_hi:[1,0] neg_lo:[0,1] neg_hi:[0,1]
	v_exp_f32_e32 v32, v32
	v_exp_f32_e32 v33, v33
	v_exp_f32_e32 v34, v34
	v_exp_f32_e32 v35, v35
	v_exp_f32_e32 v36, v36
	v_exp_f32_e32 v37, v37
	v_exp_f32_e32 v38, v38
	v_exp_f32_e32 v39, v39
	s_nop 0
	v_pk_add_f32 v[40:41], v[32:33], v[34:35]
	v_pk_add_f32 v[40:41], v[40:41], v[36:37]
	v_pk_add_f32 v[40:41], v[40:41], v[38:39]
	v_add_f32_e32 v40, v40, v41
	v_add_f32_e32 v49, v49, v40
	v_cvt_pk_bf16_f32 v32, v32, v33
	v_cvt_pk_bf16_f32 v33, v34, v35
	v_cvt_pk_bf16_f32 v34, v36, v37
	v_cvt_pk_bf16_f32 v35, v38, v39
	s_nop 1
	v_mfma_f32_16x16x32_bf16 v[0:3], v[76:79], v[32:35], v[0:3]
	v_mfma_f32_16x16x32_bf16 v[4:7], v[80:83], v[32:35], v[4:7]
	v_mfma_f32_16x16x32_bf16 v[8:11], v[84:87], v[32:35], v[8:11]
	v_mfma_f32_16x16x32_bf16 v[12:15], v[92:95], v[32:35], v[12:15]
	v_pk_fma_f32 v[144:145], v[144:145], s[40:41], v[152:153] op_sel_hi:[1,0,1]
	v_pk_fma_f32 v[146:147], v[146:147], s[40:41], v[154:155] op_sel_hi:[1,0,1]
	v_pk_fma_f32 v[148:149], v[148:149], s[40:41], v[156:157] op_sel_hi:[1,0,1]
	v_pk_fma_f32 v[150:151], v[150:151], s[40:41], v[158:159] op_sel_hi:[1,0,1]
	v_max3_f32 v152, v144, v145, v146
	v_max3_f32 v153, v147, v148, v149
	v_max3_f32 v152, v152, v150, v151
	v_max_f32_e32 v152, v152, v153
	v_cmp_gt_f32_e32 vcc, v152, v160
	s_cbranch_vccz .Lw_norescB
	v_mov_b32_e32 v153, v152
	s_nop 1
	v_permlane16_swap_b32_e32 v153, v152
	v_max_f32_e32 v152, v152, v153
	v_mov_b32_e32 v153, v152
	s_nop 1
	v_permlane32_swap_b32_e32 v153, v152
	v_max_f32_e32 v154, v152, v153
	v_max_f32_e32 v154, v160, v154
	v_sub_f32_e32 v152, v160, v154
	v_exp_f32_e32 v152, v152
	v_mov_b32_e32 v160, v154
	s_nop 0
	v_pk_mul_f32 v[104:105], v[104:105], v[152:153] op_sel_hi:[1,0]
	v_pk_mul_f32 v[106:107], v[106:107], v[152:153] op_sel_hi:[1,0]
	v_pk_mul_f32 v[108:109], v[108:109], v[152:153] op_sel_hi:[1,0]
	v_pk_mul_f32 v[110:111], v[110:111], v[152:153] op_sel_hi:[1,0]
	v_pk_mul_f32 v[112:113], v[112:113], v[152:153] op_sel_hi:[1,0]
	v_pk_mul_f32 v[114:115], v[114:115], v[152:153] op_sel_hi:[1,0]
	v_pk_mul_f32 v[116:117], v[116:117], v[152:153] op_sel_hi:[1,0]
	v_pk_mul_f32 v[118:119], v[118:119], v[152:153] op_sel_hi:[1,0]
	v_mul_f32_e32 v161, v161, v152

.Lb_pfgoA:
	s_lshl_b32 s1, 0x12000, s37
	s_mul_i32 s0, s12, s1
	s_add_u32 s16, s24, s0
	s_addc_u32 s17, s25, 0
	s_add_u32 s20, s26, s0
	s_addc_u32 s21, s27, 0
	s_add_i32 s2, s12, 1
	s_cmp_gt_i32 s2, s36
	s_cselect_b32 s2, s12, s2
	s_mul_i32 s0, s2, s1
	s_add_u32 s18, s24, s0
	s_addc_u32 s19, s25, 0
	s_add_u32 s22, s26, s0
	s_addc_u32 s23, s27, 0
	global_load_dwordx4 v[24:27], v111, s[16:17]
	global_load_dwordx4 v[28:31], v111, s[16:17] offset:64
	global_load_dwordx4 v[32:35], v111, s[18:19]
	global_load_dwordx4 v[36:39], v111, s[18:19] offset:64
	global_load_dwordx4 v[40:43], v112, s[20:21]
	global_load_dwordx4 v[44:47], v113, s[20:21]
	global_load_dwordx4 v[48:51], v112, s[22:23]
	global_load_dwordx4 v[52:55], v113, s[22:23]
	s_waitcnt lgkmcnt(0)
	ds_read_u16 v56, v115 offset:0
	ds_read_u16 v74, v115 offset:144
	ds_read_u16 v57, v115 offset:288
	ds_read_u16 v75, v115 offset:432
	ds_read_u16 v60, v115 offset:32
	ds_read_u16 v78, v115 offset:176
	ds_read_u16 v61, v115 offset:320
	ds_read_u16 v79, v115 offset:464
	ds_read_u16 v66, v115 offset:64
	ds_read_u16 v82, v115 offset:208
	ds_read_u16 v67, v115 offset:352
	ds_read_u16 v83, v115 offset:496
	ds_read_u16 v70, v115 offset:96
	ds_read_u16 v86, v115 offset:240
	ds_read_u16 v71, v115 offset:384
	ds_read_u16 v87, v115 offset:528
	ds_read_u16 v58, v115 offset:2304
	ds_read_u16 v76, v115 offset:2448
	ds_read_u16 v59, v115 offset:2592
	ds_read_u16 v77, v115 offset:2736
	ds_read_u16 v62, v115 offset:2336
	ds_read_u16 v80, v115 offset:2480
	ds_read_u16 v63, v115 offset:2624
	ds_read_u16 v81, v115 offset:2768
	ds_read_u16 v68, v115 offset:2368
	ds_read_u16 v84, v115 offset:2512
	ds_read_u16 v69, v115 offset:2656
	ds_read_u16 v85, v115 offset:2800
	ds_read_u16 v72, v115 offset:2400
	ds_read_u16 v88, v115 offset:2544
	ds_read_u16 v73, v115 offset:2688
	ds_read_u16 v89, v115 offset:2832
	v_pk_fma_f32 v[92:93], v[92:93], s[40:41], v[100:101] op_sel_hi:[1,0,1]
	v_pk_fma_f32 v[94:95], v[94:95], s[40:41], v[102:103] op_sel_hi:[1,0,1]
	v_pk_fma_f32 v[96:97], v[96:97], s[40:41], v[104:105] op_sel_hi:[1,0,1]
	v_pk_fma_f32 v[98:99], v[98:99], s[40:41], v[106:107] op_sel_hi:[1,0,1]
	v_max3_f32 v100, v92, v93, v94
	v_max3_f32 v101, v95, v96, v97
	v_max3_f32 v100, v100, v98, v99
	v_max_f32_e32 v100, v100, v101
	v_cmp_gt_f32_e32 vcc, v100, v108
	s_cbranch_vccz .Lb_norescAA
	v_mov_b32_e32 v101, v100
	s_nop 1
	v_permlane16_swap_b32_e32 v101, v100
	v_max_f32_e32 v100, v100, v101
	v_mov_b32_e32 v101, v100
	s_nop 1
	v_permlane32_swap_b32_e32 v101, v100
	v_max_f32_e32 v102, v100, v101
	v_max_f32_e32 v102, v108, v102
	v_sub_f32_e32 v100, v108, v102
	v_exp_f32_e32 v100, v100
	v_mov_b32_e32 v108, v102
	s_nop 0
	v_pk_mul_f32 v[0:1], v[0:1], v[100:101] op_sel_hi:[1,0]
	v_pk_mul_f32 v[2:3], v[2:3], v[100:101] op_sel_hi:[1,0]
	v_pk_mul_f32 v[4:5], v[4:5], v[100:101] op_sel_hi:[1,0]
	v_pk_mul_f32 v[6:7], v[6:7], v[100:101] op_sel_hi:[1,0]
	v_pk_mul_f32 v[8:9], v[8:9], v[100:101] op_sel_hi:[1,0]
	v_pk_mul_f32 v[10:11], v[10:11], v[100:101] op_sel_hi:[1,0]
	v_pk_mul_f32 v[12:13], v[12:13], v[100:101] op_sel_hi:[1,0]
	v_pk_mul_f32 v[14:15], v[14:15], v[100:101] op_sel_hi:[1,0]
	v_mul_f32_e32 v109, v109, v100
.Lb_norescAA:
	v_pk_add_f32 v[92:93], v[92:93], v[108:109] op_sel_hi:[1,0] neg_lo:[0,1] neg_hi:[0,1]
	v_pk_add_f32 v[94:95], v[94:95], v[108:109] op_sel_hi:[1,0] neg_lo:[0,1] neg_hi:[0,1]
	v_pk_add_f32 v[96:97], v[96:97], v[108:109] op_sel_hi:[1,0] neg_lo:[0,1] neg_hi:[0,1]
	v_pk_add_f32 v[98:99], v[98:99], v[108:109] op_sel_hi:[1,0] neg_lo:[0,1] neg_hi:[0,1]
	v_exp_f32_e32 v92, v92
	v_exp_f32_e32 v93, v93
	v_exp_f32_e32 v94, v94
	v_exp_f32_e32 v95, v95
	v_exp_f32_e32 v96, v96
	v_exp_f32_e32 v97, v97
	v_exp_f32_e32 v98, v98
	v_exp_f32_e32 v99, v99
	s_nop 0
	v_pk_add_f32 v[100:101], v[92:93], v[94:95]
	v_pk_add_f32 v[100:101], v[100:101], v[96:97]
	v_pk_add_f32 v[100:101], v[100:101], v[98:99]
	v_add_f32_e32 v100, v100, v101
	v_add_f32_e32 v109, v109, v100
	v_cvt_pk_bf16_f32 v92, v92, v93
	v_cvt_pk_bf16_f32 v93, v94, v95
	v_cvt_pk_bf16_f32 v94, v96, v97
	v_cvt_pk_bf16_f32 v95, v98, v99
	s_waitcnt lgkmcnt(0)
	v_lshl_or_b32 v56, v74, 16, v56
	v_lshl_or_b32 v57, v75, 16, v57
	v_lshl_or_b32 v58, v76, 16, v58
	v_lshl_or_b32 v59, v77, 16, v59
	v_lshl_or_b32 v60, v78, 16, v60
	v_lshl_or_b32 v61, v79, 16, v61
	v_lshl_or_b32 v62, v80, 16, v62
	v_lshl_or_b32 v63, v81, 16, v63
	v_lshl_or_b32 v66, v82, 16, v66
	v_lshl_or_b32 v67, v83, 16, v67
	v_lshl_or_b32 v68, v84, 16, v68
	v_lshl_or_b32 v69, v85, 16, v69
	v_lshl_or_b32 v70, v86, 16, v70
	v_lshl_or_b32 v71, v87, 16, v71
	v_lshl_or_b32 v72, v88, 16, v72
	v_lshl_or_b32 v73, v89, 16, v73
	s_nop 1
	v_mfma_f32_16x16x32_bf16 v[0:3], v[56:59], v[92:95], v[0:3]
	v_mfma_f32_16x16x32_bf16 v[4:7], v[60:63], v[92:95], v[4:7]
	v_mfma_f32_16x16x32_bf16 v[8:11], v[66:69], v[92:95], v[8:11]
	v_mfma_f32_16x16x32_bf16 v[12:15], v[70:73], v[92:95], v[12:15]
	v_pk_fma_f32 v[132:133], v[132:133], s[40:41], v[124:125] op_sel_hi:[1,0,1]
	v_pk_fma_f32 v[134:135], v[134:135], s[40:41], v[126:127] op_sel_hi:[1,0,1]
	v_pk_fma_f32 v[136:137], v[136:137], s[40:41], v[128:129] op_sel_hi:[1,0,1]
	v_pk_fma_f32 v[138:139], v[138:139], s[40:41], v[130:131] op_sel_hi:[1,0,1]
	v_max3_f32 v124, v132, v133, v134
	v_max3_f32 v125, v135, v136, v137
	v_max3_f32 v124, v124, v138, v139
	v_max_f32_e32 v124, v124, v125
	v_cmp_gt_f32_e32 vcc, v124, v168
	s_cbranch_vccz .Lb_norescBA
	v_mov_b32_e32 v125, v124
	s_nop 1
	v_permlane16_swap_b32_e32 v125, v124
	v_max_f32_e32 v124, v124, v125
	v_mov_b32_e32 v125, v124
	s_nop 1
	v_permlane32_swap_b32_e32 v125, v124
	v_max_f32_e32 v126, v124, v125
	v_max_f32_e32 v126, v168, v126
	v_sub_f32_e32 v124, v168, v126
	v_exp_f32_e32 v124, v124
	v_mov_b32_e32 v168, v126
	s_nop 0
	v_pk_mul_f32 v[144:145], v[144:145], v[124:125] op_sel_hi:[1,0]
	v_pk_mul_f32 v[146:147], v[146:147], v[124:125] op_sel_hi:[1,0]
	v_pk_mul_f32 v[148:149], v[148:149], v[124:125] op_sel_hi:[1,0]
	v_pk_mul_f32 v[150:151], v[150:151], v[124:125] op_sel_hi:[1,0]
	v_pk_mul_f32 v[152:153], v[152:153], v[124:125] op_sel_hi:[1,0]
	v_pk_mul_f32 v[154:155], v[154:155], v[124:125] op_sel_hi:[1,0]
	v_pk_mul_f32 v[156:157], v[156:157], v[124:125] op_sel_hi:[1,0]
	v_pk_mul_f32 v[158:159], v[158:159], v[124:125] op_sel_hi:[1,0]
	v_mul_f32_e32 v169, v169, v124

.Lb_pfgoB:
	s_lshl_b32 s1, 0x12000, s37
	s_mul_i32 s0, s12, s1
	s_add_u32 s16, s24, s0
	s_addc_u32 s17, s25, 0
	s_add_u32 s20, s26, s0
	s_addc_u32 s21, s27, 0
	s_add_i32 s2, s12, 1
	s_cmp_gt_i32 s2, s36
	s_cselect_b32 s2, s12, s2
	s_mul_i32 s0, s2, s1
	s_add_u32 s18, s24, s0
	s_addc_u32 s19, s25, 0
	s_add_u32 s22, s26, s0
	s_addc_u32 s23, s27, 0
	global_load_dwordx4 v[172:175], v111, s[16:17]
	global_load_dwordx4 v[176:179], v111, s[16:17] offset:64
	global_load_dwordx4 v[180:183], v111, s[18:19]
	global_load_dwordx4 v[184:187], v111, s[18:19] offset:64
	global_load_dwordx4 v[188:191], v112, s[20:21]
	global_load_dwordx4 v[192:195], v113, s[20:21]
	global_load_dwordx4 v[196:199], v112, s[22:23]
	global_load_dwordx4 v[200:203], v113, s[22:23]
	s_waitcnt lgkmcnt(0)
	ds_read_u16 v56, v115 offset:0
	ds_read_u16 v74, v115 offset:144
	ds_read_u16 v57, v115 offset:288
	ds_read_u16 v75, v115 offset:432
	ds_read_u16 v60, v115 offset:32
	ds_read_u16 v78, v115 offset:176
	ds_read_u16 v61, v115 offset:320
	ds_read_u16 v79, v115 offset:464
	ds_read_u16 v66, v115 offset:64
	ds_read_u16 v82, v115 offset:208
	ds_read_u16 v67, v115 offset:352
	ds_read_u16 v83, v115 offset:496
	ds_read_u16 v70, v115 offset:96
	ds_read_u16 v86, v115 offset:240
	ds_read_u16 v71, v115 offset:384
	ds_read_u16 v87, v115 offset:528
	ds_read_u16 v58, v115 offset:2304
	ds_read_u16 v76, v115 offset:2448
	ds_read_u16 v59, v115 offset:2592
	ds_read_u16 v77, v115 offset:2736
	ds_read_u16 v62, v115 offset:2336
	ds_read_u16 v80, v115 offset:2480
	ds_read_u16 v63, v115 offset:2624
	ds_read_u16 v81, v115 offset:2768
	ds_read_u16 v68, v115 offset:2368
	ds_read_u16 v84, v115 offset:2512
	ds_read_u16 v69, v115 offset:2656
	ds_read_u16 v85, v115 offset:2800
	ds_read_u16 v72, v115 offset:2400
	ds_read_u16 v88, v115 offset:2544
	ds_read_u16 v73, v115 offset:2688
	ds_read_u16 v89, v115 offset:2832
	v_pk_fma_f32 v[92:93], v[92:93], s[40:41], v[100:101] op_sel_hi:[1,0,1]
	v_pk_fma_f32 v[94:95], v[94:95], s[40:41], v[102:103] op_sel_hi:[1,0,1]
	v_pk_fma_f32 v[96:97], v[96:97], s[40:41], v[104:105] op_sel_hi:[1,0,1]
	v_pk_fma_f32 v[98:99], v[98:99], s[40:41], v[106:107] op_sel_hi:[1,0,1]
	v_max3_f32 v100, v92, v93, v94
	v_max3_f32 v101, v95, v96, v97
	v_max3_f32 v100, v100, v98, v99
	v_max_f32_e32 v100, v100, v101
	v_cmp_gt_f32_e32 vcc, v100, v108
	s_cbranch_vccz .Lb_norescAB
	v_mov_b32_e32 v101, v100
	s_nop 1
	v_permlane16_swap_b32_e32 v101, v100
	v_max_f32_e32 v100, v100, v101
	v_mov_b32_e32 v101, v100
	s_nop 1
	v_permlane32_swap_b32_e32 v101, v100
	v_max_f32_e32 v102, v100, v101
	v_max_f32_e32 v102, v108, v102
	v_sub_f32_e32 v100, v108, v102
	v_exp_f32_e32 v100, v100
	v_mov_b32_e32 v108, v102
	s_nop 0
	v_pk_mul_f32 v[0:1], v[0:1], v[100:101] op_sel_hi:[1,0]
	v_pk_mul_f32 v[2:3], v[2:3], v[100:101] op_sel_hi:[1,0]
	v_pk_mul_f32 v[4:5], v[4:5], v[100:101] op_sel_hi:[1,0]
	v_pk_mul_f32 v[6:7], v[6:7], v[100:101] op_sel_hi:[1,0]
	v_pk_mul_f32 v[8:9], v[8:9], v[100:101] op_sel_hi:[1,0]
	v_pk_mul_f32 v[10:11], v[10:11], v[100:101] op_sel_hi:[1,0]
	v_pk_mul_f32 v[12:13], v[12:13], v[100:101] op_sel_hi:[1,0]
	v_pk_mul_f32 v[14:15], v[14:15], v[100:101] op_sel_hi:[1,0]
	v_mul_f32_e32 v109, v109, v100
